# P0 rope-table loop: 4 pos loads prefetched before loop, in-loop vmcnt(0) removed
# speedup vs baseline: 1.0283x; 1.0008x over previous
.LBB0_58:
	s_or_b64 exec, exec, s[0:1]
	s_mov_b32 s0, 0x80000
	v_cmp_gt_i32_e32 vcc, s0, v6
	s_and_saveexec_b64 s[0:1], vcc
	s_cbranch_execz .LBB0_69
	v_and_b32_e32 v1, 31, v69
	s_mov_b32 s2, 0xbbb55516
	v_cvt_f64_u32_e32 v[2:3], v1
	s_mov_b32 s3, 0xbfd26bb1
	v_mul_f64 v[8:9], v[2:3], s[2:3]
	s_mov_b32 s2, 0x652b82fe
	s_mov_b32 s3, 0x3ff71547
	v_mul_f64 v[2:3], v[8:9], s[2:3]
	s_mov_b32 s2, 0xfefa39ef
	v_rndne_f64_e32 v[10:11], v[2:3]
	s_mov_b32 s3, 0xbfe62e42
	v_fma_f64 v[12:13], s[2:3], v[10:11], v[8:9]
	s_mov_b32 s2, 0x3b39803f
	s_mov_b32 s3, 0xbc7abc9e
	v_fmac_f64_e32 v[12:13], s[2:3], v[10:11]
	s_mov_b32 s2, 0x6a5dcb37
	v_mov_b32_e32 v2, 0xfca7ab0c
	v_mov_b32_e32 v3, 0x3e928af3
	s_mov_b32 s3, 0x3e5ade15
	v_fmac_f64_e32 v[2:3], s[2:3], v[12:13]
	v_mov_b32_e32 v4, 0x623fde64
	v_mov_b32_e32 v5, 0x3ec71dee
	v_fmac_f64_e32 v[4:5], v[12:13], v[2:3]
	v_mov_b32_e32 v2, 0x7c89e6b0
	v_mov_b32_e32 v3, 0x3efa0199
	v_fmac_f64_e32 v[2:3], v[12:13], v[4:5]
	v_mov_b32_e32 v4, 0x14761f6e
	v_mov_b32_e32 v5, 0x3f2a01a0
	v_fmac_f64_e32 v[4:5], v[12:13], v[2:3]
	v_mov_b32_e32 v14, 0x1852b7b0
	v_mov_b32_e32 v15, 0x3f56c16c
	v_mov_b32_e32 v2, 0x11122322
	v_mov_b32_e32 v3, 0x3f811111
	v_fmac_f64_e32 v[14:15], v[12:13], v[4:5]
	v_mov_b64_e32 v[16:17], v[2:3]
	v_mov_b32_e32 v4, 0x555502a1
	v_mov_b32_e32 v5, 0x3fa55555
	v_fmac_f64_e32 v[16:17], v[12:13], v[14:15]
	v_mov_b64_e32 v[14:15], v[4:5]
	v_fmac_f64_e32 v[14:15], v[12:13], v[16:17]
	v_mov_b32_e32 v16, 0x55555511
	v_mov_b32_e32 v17, 0x3fc55555
	v_fmac_f64_e32 v[16:17], v[12:13], v[14:15]
	v_mov_b32_e32 v14, 11
	v_mov_b32_e32 v15, 0x3fe00000
	s_mov_b32 s2, 0
	v_fmac_f64_e32 v[14:15], v[12:13], v[16:17]
	s_mov_b32 s3, 0x40900000
	v_fma_f64 v[14:15], v[12:13], v[14:15], 1.0
	v_cmp_nlt_f64_e32 vcc, s[2:3], v[8:9]
	s_mov_b32 s2, 0
	v_fma_f64 v[12:13], v[12:13], v[14:15], 1.0
	v_cvt_i32_f64_e32 v1, v[10:11]
	s_mov_b32 s3, 0xc090cc00
	v_ldexp_f64 v[10:11], v[12:13], v1
	v_mov_b32_e32 v1, 0x7ff00000
	v_cmp_ngt_f64_e64 s[2:3], s[2:3], v[8:9]
	v_cndmask_b32_e32 v1, v1, v11, vcc
	s_and_b64 vcc, s[2:3], vcc
	v_cndmask_b32_e64 v9, 0, v1, s[2:3]
	v_cndmask_b32_e32 v8, 0, v10, vcc
	v_cvt_f32_f64_e32 v1, v[8:9]
	v_lshl_add_u64 v[8:9], v[6:7], 2, s[90:91]
	s_mov_b64 s[2:3], 0x1e400000
	s_ashr_i32 s53, s52, 31
	s_mov_b32 s20, 0x6dc9c883
	s_mov_b32 s34, 0x54442d18
	s_mov_b32 s56, 0x67f544e4
	v_mov_b32_e32 v12, 0x1a01a01a
	v_mov_b32_e32 v14, 0x55555555
	s_mov_b32 s58, 0xeff8d898
	v_lshl_add_u64 v[8:9], v[8:9], 0, s[2:3]
	s_lshl_b64 s[2:3], s[52:53], 2
	s_mov_b64 s[4:5], 0
	s_mov_b32 s21, 0x3fe45f30
	s_mov_b32 s35, 0xbff921fb
	v_mov_b32_e32 v10, 0xa556c734
	v_mov_b32_e32 v11, 0x3ec71de3
	s_mov_b32 s57, 0xbe5ae645
	v_mov_b32_e32 v13, 0xbf2a01a0
	v_mov_b32_e32 v2, 0x11111111
	v_mov_b32_e32 v15, 0xbfc55555
	v_mov_b32_e32 v16, 0xb7789f5c
	v_mov_b32_e32 v17, 0xbe927e4f
	s_mov_b32 s59, 0x3e21eed8
	v_mov_b32_e32 v19, 0x3efa01a0
	v_mov_b32_e32 v18, v12
	v_mov_b32_e32 v20, 0x16c16c17
	v_mov_b32_e32 v21, 0xbf56c16c
	v_mov_b32_e32 v4, v14
	s_mov_b32 s12, 0x7ffff
	v_readlane_b32 s38, v246, 22
	v_readlane_b32 s39, v246, 23
	v_ashrrev_i32_e32 v134, 5, v6
	v_add_u32_e32 v138, s52, v6
	v_ashrrev_i32_e32 v135, 5, v138
	v_add_u32_e32 v138, s52, v138
	v_ashrrev_i32_e32 v136, 5, v138
	v_add_u32_e32 v138, s52, v138
	v_ashrrev_i32_e32 v137, 5, v138
	v_lshlrev_b32_e32 v134, 2, v134
	v_lshlrev_b32_e32 v135, 2, v135
	v_lshlrev_b32_e32 v136, 2, v136
	v_lshlrev_b32_e32 v137, 2, v137
	global_load_dword v134, v134, s[38:39]
	global_load_dword v135, v135, s[38:39]
	global_load_dword v136, v136, s[38:39]
	global_load_dword v137, v137, s[38:39]
	s_waitcnt vmcnt(0)
	s_branch .LBB0_62

.LBB0_62:
	v_ashrrev_i32_e32 v22, 5, v6
	v_readlane_b32 s36, v246, 20
	v_ashrrev_i32_e32 v23, 31, v22
	v_readlane_b32 s38, v246, 22
	v_readlane_b32 s39, v246, 23
	v_readlane_b32 s37, v246, 21
	v_readlane_b32 s40, v246, 24
	v_lshl_add_u64 v[22:23], v[22:23], 2, s[38:39]
	v_mov_b32_e32 v7, v134
	v_mov_b32_e32 v134, v135
	v_mov_b32_e32 v135, v136
	v_mov_b32_e32 v136, v137
	v_readlane_b32 s41, v246, 25
	v_readlane_b32 s42, v246, 26
	v_readlane_b32 s43, v246, 27
	v_readlane_b32 s44, v246, 28
	v_readlane_b32 s45, v246, 29
	v_readlane_b32 s46, v246, 30
	v_readlane_b32 s47, v246, 31
	v_readlane_b32 s48, v246, 32
	v_readlane_b32 s49, v246, 33
	v_readlane_b32 s50, v246, 34
	v_readlane_b32 s51, v246, 35
	s_nop 0
	v_cvt_f32_i32_e32 v7, v7
	v_mul_f32_e32 v7, v1, v7
	v_cvt_f64_f32_e32 v[22:23], v7
	v_mul_f64 v[24:25], v[22:23], s[20:21]
	v_rndne_f64_e32 v[24:25], v[24:25]
	v_fmac_f64_e32 v[22:23], s[34:35], v[24:25]
	v_mul_f64 v[26:27], v[22:23], v[22:23]
	v_cvt_i32_f64_e32 v7, v[24:25]
	v_fma_f64 v[24:25], s[56:57], v[26:27], v[10:11]
	v_fma_f64 v[28:29], s[58:59], v[26:27], v[16:17]
	v_fma_f64 v[24:25], v[26:27], v[24:25], v[12:13]
	v_fma_f64 v[28:29], v[26:27], v[28:29], v[18:19]
	v_fma_f64 v[24:25], v[26:27], v[24:25], v[2:3]
	v_fma_f64 v[28:29], v[26:27], v[28:29], v[20:21]
	v_fma_f64 v[24:25], v[26:27], v[24:25], v[14:15]
	v_fma_f64 v[28:29], v[26:27], v[28:29], v[4:5]
	v_and_b32_e32 v7, 3, v7
	v_fma_f64 v[24:25], v[26:27], v[24:25], 1.0
	v_fma_f64 v[28:29], v[26:27], v[28:29], -0.5
	v_mul_f64 v[24:25], v[22:23], v[24:25]
	v_fma_f64 v[22:23], v[26:27], v[28:29], 1.0
	v_cmp_lt_i32_e32 vcc, 1, v7
	s_and_saveexec_b64 s[8:9], vcc
	s_xor_b64 s[8:9], exec, s[8:9]
	s_cbranch_execz .LBB0_66
	v_cmp_lt_i32_e32 vcc, 2, v7
	v_xor_b32_e32 v27, 0x80000000, v25
	v_mov_b32_e32 v26, v24
	v_xor_b32_e32 v23, 0x80000000, v23
	s_and_saveexec_b64 s[10:11], vcc
	s_xor_b64 s[10:11], exec, s[10:11]
	v_mov_b64_e32 v[26:27], v[22:23]
	v_mov_b64_e32 v[22:23], v[24:25]
	s_andn2_saveexec_b64 s[10:11], s[10:11]
	s_or_b64 exec, exec, s[10:11]
